# FFN-up K-loop: fragment ds_reads of the next K-step interleaved into the MFMA shadow (two spare VGPRs as address temporaries, lgkmcnt re-derived)
# baseline (speedup 1.0000x reference)
.LBB0_853:
	s_and_b32 s14, s7, 0x10000
	s_add_i32 s6, s14, 0
	v_add_u32_e32 v0, s6, v195
	v_add3_u32 v174, v0, v218, v219
	v_add3_u32 v0, v0, v220, v219
	s_xor_b32 s14, s14, 0x10000
	ds_read_b128 v[162:165], v174
	ds_read_b128 v[166:169], v174 offset:4096
	ds_read_b128 v[178:181], v174 offset:8192
	ds_read_b128 v[182:185], v174 offset:12288
	ds_read_b128 v[190:193], v0 offset:32768
	ds_read_b128 v[246:249], v0 offset:36864
	v_add_u32_e32 v0, s14, v194
	s_waitcnt vmcnt(7)
	ds_write_b128 v0, v[142:145]
	s_waitcnt vmcnt(6)
	ds_write_b128 v0, v[158:161] offset:32768
	v_lshl_add_u64 v[176:177], v[170:171], 0, s[8:9]
	v_lshl_add_u64 v[174:175], v[172:173], 0, s[8:9]
	global_load_dwordx4 v[142:145], v[176:177], off offset:256
	global_load_dwordx4 v[158:161], v[174:175], off offset:256
	s_waitcnt lgkmcnt(3)
	v_mfma_f32_32x32x16_bf16 v[114:129], v[162:165], v[190:193], v[114:129]
	v_mfma_f32_32x32x16_bf16 v[82:97], v[166:169], v[190:193], v[82:97]
	v_mfma_f32_32x32x16_bf16 v[50:65], v[178:181], v[190:193], v[50:65]
	v_mfma_f32_32x32x16_bf16 v[18:33], v[182:185], v[190:193], v[18:33]
	v_add_u32_e32 v250, s6, v215
	v_add3_u32 v245, v250, v220, v219
	v_add3_u32 v251, v250, v218, v219
	ds_read_b128 v[190:193], v245 offset:32768
	s_waitcnt lgkmcnt(3)
	v_mfma_f32_32x32x16_bf16 v[98:113], v[162:165], v[246:249], v[98:113]
	ds_read_b128 v[162:165], v251
	v_mfma_f32_32x32x16_bf16 v[66:81], v[166:169], v[246:249], v[66:81]
	ds_read_b128 v[166:169], v251 offset:4096
	v_mfma_f32_32x32x16_bf16 v[34:49], v[178:181], v[246:249], v[34:49]
	ds_read_b128 v[178:181], v251 offset:8192
	v_mfma_f32_32x32x16_bf16 v[2:17], v[182:185], v[246:249], v[2:17]
	ds_read_b128 v[182:185], v251 offset:12288
	ds_read_b128 v[246:249], v245 offset:36864
	s_waitcnt vmcnt(7)
	ds_write_b128 v0, v[138:141] offset:8192
	s_waitcnt vmcnt(6)
	ds_write_b128 v0, v[154:157] offset:40960
	v_add_co_u32_e32 v138, vcc, s23, v176
	s_nop 1
	v_addc_co_u32_e32 v139, vcc, 0, v177, vcc
	v_add_co_u32_e32 v154, vcc, s25, v174
	global_load_dwordx4 v[138:141], v[138:139], off offset:256
	s_nop 0
	v_addc_co_u32_e32 v155, vcc, 0, v175, vcc
	global_load_dwordx4 v[154:157], v[154:155], off offset:256
	s_waitcnt lgkmcnt(6)
	v_mfma_f32_32x32x16_bf16 v[114:129], v[162:165], v[190:193], v[114:129]
	s_waitcnt lgkmcnt(5)
	v_mfma_f32_32x32x16_bf16 v[82:97], v[166:169], v[190:193], v[82:97]
	s_waitcnt lgkmcnt(4)
	v_mfma_f32_32x32x16_bf16 v[50:65], v[178:181], v[190:193], v[50:65]
	s_waitcnt lgkmcnt(3)
	v_mfma_f32_32x32x16_bf16 v[18:33], v[182:185], v[190:193], v[18:33]
	v_add_u32_e32 v250, s6, v216
	v_add3_u32 v245, v250, v220, v219
	v_add3_u32 v251, v250, v218, v219
	ds_read_b128 v[190:193], v245 offset:32768
	s_waitcnt lgkmcnt(3)
	v_mfma_f32_32x32x16_bf16 v[98:113], v[162:165], v[246:249], v[98:113]
	ds_read_b128 v[162:165], v251
	v_mfma_f32_32x32x16_bf16 v[66:81], v[166:169], v[246:249], v[66:81]
	ds_read_b128 v[166:169], v251 offset:4096
	v_mfma_f32_32x32x16_bf16 v[34:49], v[178:181], v[246:249], v[34:49]
	ds_read_b128 v[178:181], v251 offset:8192
	v_mfma_f32_32x32x16_bf16 v[2:17], v[182:185], v[246:249], v[2:17]
	ds_read_b128 v[182:185], v251 offset:12288
	ds_read_b128 v[246:249], v245 offset:36864
	s_waitcnt vmcnt(7)
	ds_write_b128 v0, v[134:137] offset:16384
	s_waitcnt vmcnt(6)
	ds_write_b128 v0, v[150:153] offset:49152
	v_add_co_u32_e32 v134, vcc, s22, v176
	s_nop 1
	v_addc_co_u32_e32 v135, vcc, 0, v177, vcc
	v_add_co_u32_e32 v150, vcc, s23, v174
	global_load_dwordx4 v[134:137], v[134:135], off offset:256
	s_nop 0
	v_addc_co_u32_e32 v151, vcc, 0, v175, vcc
	global_load_dwordx4 v[150:153], v[150:151], off offset:256
	s_waitcnt lgkmcnt(3)
	v_mfma_f32_32x32x16_bf16 v[82:97], v[166:169], v[190:193], v[82:97]
	s_waitcnt lgkmcnt(2)
	v_mfma_f32_32x32x16_bf16 v[66:81], v[166:169], v[246:249], v[66:81]
	v_add_u32_e32 v166, s6, v217
	v_mfma_f32_32x32x16_bf16 v[114:129], v[162:165], v[190:193], v[114:129]
	v_mfma_f32_32x32x16_bf16 v[98:113], v[162:165], v[246:249], v[98:113]
	v_add3_u32 v162, v166, v218, v219
	v_add3_u32 v166, v166, v220, v219
	v_mfma_f32_32x32x16_bf16 v[50:65], v[178:181], v[190:193], v[50:65]
	v_mfma_f32_32x32x16_bf16 v[34:49], v[178:181], v[246:249], v[34:49]
	v_mfma_f32_32x32x16_bf16 v[18:33], v[182:185], v[190:193], v[18:33]
	v_mfma_f32_32x32x16_bf16 v[2:17], v[182:185], v[246:249], v[2:17]
	ds_read_b128 v[178:181], v162
	ds_read_b128 v[182:185], v162 offset:4096
	ds_read_b128 v[190:193], v162 offset:8192
	ds_read_b128 v[162:165], v162 offset:12288
	ds_read_b128 v[246:249], v166 offset:32768
	ds_read_b128 v[166:169], v166 offset:36864
	s_waitcnt vmcnt(7)
	ds_write_b128 v0, v[130:133] offset:24576
	s_waitcnt vmcnt(6)
	ds_write_b128 v0, v[146:149] offset:57344
	v_add_co_u32_e32 v130, vcc, s24, v176
	s_nop 1
	v_addc_co_u32_e32 v131, vcc, 0, v177, vcc
	v_add_co_u32_e32 v146, vcc, s26, v174
	global_load_dwordx4 v[130:133], v[130:131], off offset:256
	s_nop 0
	v_addc_co_u32_e32 v147, vcc, 0, v175, vcc
	global_load_dwordx4 v[146:149], v[146:147], off offset:256
	s_waitcnt lgkmcnt(3)
	v_mfma_f32_32x32x16_bf16 v[114:129], v[178:181], v[246:249], v[114:129]
	s_add_u32 s8, s8, 0x80
	s_addc_u32 s9, s9, 0
	s_add_i32 s7, s7, 0x10000
	s_cmpk_eq_i32 s8, 0x700
	s_waitcnt lgkmcnt(0)
	s_barrier
	v_mfma_f32_32x32x16_bf16 v[98:113], v[178:181], v[166:169], v[98:113]
	v_mfma_f32_32x32x16_bf16 v[82:97], v[182:185], v[246:249], v[82:97]
	v_mfma_f32_32x32x16_bf16 v[66:81], v[182:185], v[166:169], v[66:81]
	v_mfma_f32_32x32x16_bf16 v[50:65], v[190:193], v[246:249], v[50:65]
	v_mfma_f32_32x32x16_bf16 v[34:49], v[190:193], v[166:169], v[34:49]
	v_mfma_f32_32x32x16_bf16 v[18:33], v[162:165], v[246:249], v[18:33]
	v_mfma_f32_32x32x16_bf16 v[2:17], v[162:165], v[166:169], v[2:17]
	s_cbranch_scc0 .LBB0_853
	ds_read_b128 v[182:185], v229
	ds_read_b128 v[178:181], v229 offset:4096
	ds_read_b128 v[166:169], v229 offset:8192
	ds_read_b128 v[162:165], v229 offset:12288
	ds_read_b128 v[170:173], v230 offset:32768
	ds_read_b128 v[174:177], v230 offset:36864
	v_cndmask_b32_e64 v0, 0, 1, s[12:13]
	v_cmp_ne_u32_e64 s[8:9], 1, v0
	s_andn2_b64 vcc, exec, s[12:13]
	v_lshl_add_u64 v[190:191], v[188:189], 1, s[10:11]
	v_lshl_add_u64 v[192:193], v[186:187], 1, s[4:5]
	s_waitcnt vmcnt(7)
	ds_write_b128 v221, v[142:145]
	s_waitcnt vmcnt(6)
	ds_write_b128 v222, v[158:161]
	s_cbranch_vccnz .LBB0_856
	global_load_dwordx4 v[142:145], v[192:193], off
	global_load_dwordx4 v[158:161], v[190:191], off
